# M3 class HGRN-sample gate prologue: 8 serialised (s_load, s_load, 2 dword loads, vmcnt(0)) steps replaced by four dwordx4 loads + one wait, same arithmetic
# baseline (speedup 1.0000x reference)
; #define LAS __attribute__((address_space(3)))
; __device__ __forceinline__ float sigmoidf_(float x) { return 1.0f / (1.0f + __expf(-x)); }
; __device__ __forceinline__ int tidx() { int t = threadIdx.x; asm volatile("" : "+v"(t)); return t; }
; __device__ __forceinline__ const float* pin(int i) { return kargs()->in[i]; }
; template <int MIX> __device__ __forceinline__ MixPar mix_par(int l, int head) {
;     MixPar m; const int cgi = tidx() & 7;
; #pragma unroll
;     for (int i = 0; i < 8; ++i) m.f[i] = 0.f;
;     if constexpr (MIX == 0) {
; #pragma unroll
;         for (int i = 0; i < 8; ++i) { const int c = head * 64 + cgi * 8 + i; m.f[i] = l == 0 ? 0.f : sigmoidf_(pin(10)[256 + c] - pin(10)[c]); }
;     ...
;     const Slot sl = slot_of<SAMPLE>(chunk, s, sg);
;     f32x4 o = *(const LAS f32x4*)(L + C::OFF_O + s * 32 + c4);
;     if constexpr (MIX == 3) o = o + *(const LAS f32x4*)(L + C::OFF_XSD + s * 32 + c4);
;     u32x2 w; w.x = pkh(o[0], o[1]); w.y = pkh(o[2], o[3]);
;     if (c4 < nv) *(u32x2*)(raw + (size_t)sl.row * DM + mixer * 256 + head * 64 + vcol0 + c4) = w;
.LBB0_202:
	s_or_b64 exec, exec, s[10:11]
	v_mov_b32_e32 v0, v202
	s_waitcnt lgkmcnt(0)
	s_barrier
	s_mov_b32 s89, s79
	v_ashrrev_i32_e32 v1, 3, v0
	v_lshlrev_b32_e32 v0, 2, v0
	v_and_b32_e32 v6, 28, v0
	v_and_b32_e32 v0, -4, v1
	v_add_u32_e32 v0, s26, v0
	v_and_or_b32 v4, v1, 3, v0
	v_lshlrev_b32_e32 v0, 7, v1
	v_lshlrev_b32_e32 v1, 2, v6
	v_add3_u32 v0, 0, v0, v1
	s_waitcnt vmcnt(0)
	ds_read_b128 v[0:3], v0 offset:50176
	v_ashrrev_i32_e32 v5, 31, v4
	v_lshlrev_b32_e32 v16, 1, v6
	s_mov_b32 s2, 0x3500000
	v_mov_b32_e32 v28, v202
	s_waitcnt lgkmcnt(0)
	v_cvt_pk_f16_f32 v0, v0, v1
	v_cvt_pk_f16_f32 v1, v2, v3
	v_lshlrev_b64 v[2:3], 11, v[4:5]
	v_lshl_add_u64 v[2:3], s[8:9], 0, v[2:3]
	v_lshl_add_u64 v[2:3], v[2:3], 0, s[78:79]
	v_lshl_add_u64 v[2:3], v[2:3], 0, s[88:89]
	v_lshl_add_u64 v[2:3], v[2:3], 0, v[16:17]
	v_add_co_u32_e32 v2, vcc, s2, v2
	s_mov_b64 s[2:3], s[0:1]
	s_nop 0
	v_addc_co_u32_e32 v3, vcc, 0, v3, vcc
	global_store_dwordx2 v[2:3], v[0:1], off offset:512
	s_barrier
	s_load_dwordx2 s[10:11], s[2:3], 0xe0
	s_mov_b64 s[2:3], s[0:1]
	s_load_dwordx2 s[8:9], s[2:3], 0xe0
	v_mov_b32_e32 v0, v202
	v_readlane_b32 s2, v252, 56
	v_lshlrev_b32_e32 v0, 3, v0
	v_readlane_b32 s3, v252, 57
	v_and_or_b32 v0, v0, 56, s83
	v_mov_b32_e32 v1, 0
	v_cndmask_b32_e64 v2, 0, 1, s[2:3]
	v_cmp_ne_u32_e64 s[42:43], 1, v2
	s_andn2_b64 vcc, exec, s[2:3]
	v_lshlrev_b32_e32 v0, 2, v0
	v_mov_b32_e32 v4, 0
	s_cbranch_vccnz .LBB0_204
	s_load_dwordx2 s[2:3], s[0:1], 0x50
	v_readlane_b32 s80, v253, 50
	v_readlane_b32 s81, v253, 51
	s_waitcnt lgkmcnt(0)
	global_load_dwordx4 v[24:27], v0, s[2:3]
	global_load_dwordx4 v[34:37], v0, s[2:3] offset:16
	global_load_dwordx4 v[30:33], v0, s[2:3] offset:1024
	global_load_dwordx4 v[10:13], v0, s[2:3] offset:1040
	s_waitcnt vmcnt(0)
	v_sub_f32_e32 v4, v30, v24
	v_sub_f32_e32 v1, v31, v25
	v_sub_f32_e32 v8, v32, v26
	v_sub_f32_e32 v3, v33, v27
	v_sub_f32_e32 v22, v10, v34
	v_sub_f32_e32 v15, v13, v37
	v_sub_f32_e32 v18, v12, v36
	v_sub_f32_e32 v13, v11, v35
	v_mul_f32_e32 v4, 0xbfb8aa3b, v4
	v_mul_f32_e32 v1, 0xbfb8aa3b, v1
	v_mul_f32_e32 v8, 0xbfb8aa3b, v8
	v_mul_f32_e32 v3, 0xbfb8aa3b, v3
	v_mul_f32_e32 v22, 0xbfb8aa3b, v22
	v_mul_f32_e32 v15, 0xbfb8aa3b, v15
	v_mul_f32_e32 v18, 0xbfb8aa3b, v18
	v_mul_f32_e32 v13, 0xbfb8aa3b, v13
	v_exp_f32_e32 v4, v4
	v_exp_f32_e32 v1, v1
	v_exp_f32_e32 v8, v8
	v_exp_f32_e32 v3, v3
	v_exp_f32_e32 v22, v22
	v_exp_f32_e32 v15, v15
	v_exp_f32_e32 v18, v18
	v_exp_f32_e32 v13, v13
	v_add_f32_e32 v4, 1.0, v4
	v_add_f32_e32 v1, 1.0, v1
	v_add_f32_e32 v8, 1.0, v8
	v_add_f32_e32 v3, 1.0, v3
	v_add_f32_e32 v22, 1.0, v22
	v_add_f32_e32 v15, 1.0, v15
	v_add_f32_e32 v18, 1.0, v18
	v_add_f32_e32 v13, 1.0, v13
	v_rcp_f32_e32 v4, v4
	v_rcp_f32_e32 v1, v1
	v_rcp_f32_e32 v8, v8
	v_rcp_f32_e32 v3, v3
	v_rcp_f32_e32 v22, v22
	v_rcp_f32_e32 v15, v15
	v_rcp_f32_e32 v18, v18
	v_rcp_f32_e32 v13, v13
	s_nop 0
	s_branch .LBB0_213
